# relaxed seam 5 with group start stagger s_sleep 14
# speedup vs baseline: 1.0251x; 1.0012x over previous
; __device__ __forceinline__ void mk_p3(const Ptrs& P, LAS unsigned char* lds, int tid, int wave, int lane, int bx, int G, bool dry) {
;     ...
;         { bool pre = false; for (int u = bx; u < NB * 32 * 4; u += G) pre = attn_unit(P, lds, u, tid, wave, lane, pre, u + G < NB * 32 * 4 ? u + G : -1); }
.Lstg_loop:
	s_cmp_eq_u32 vcc_lo, 0
	s_cbranch_scc1 .Lstg_done
	s_sleep 14
	s_sub_u32 vcc_lo, vcc_lo, 1
	s_branch .Lstg_loop
